# write-through (sc1) on the 8-byte row-phase stores of P1/P4/P8 (less dirty L2 at the next grid barrier)
# speedup vs baseline: 1.0435x; 1.0010x over previous
.LBB0_97:
	s_and_b64 s[0:1], s[0:1], exec
	s_cselect_b32 s1, s7, 0
	s_cselect_b32 s0, s6, s19
	s_cselect_b32 s19, s53, s55
	s_cselect_b32 s20, s52, s54
	s_lshl_b64 s[0:1], s[0:1], 12
	s_add_u32 s0, s20, s0
	s_addc_u32 s1, s19, s1
	global_load_dwordx4 v[50:53], v49, s[0:1]
	global_load_dwordx4 v[54:57], v49, s[0:1] offset:1024
	global_load_dwordx4 v[58:61], v49, s[0:1] offset:3072
	global_load_dwordx4 v[62:65], v49, s[0:1] offset:2048
	s_add_u32 s6, s6, s8
	s_addc_u32 s7, s7, s9
	s_cmpk_lt_i32 s6, 0x2800
	s_waitcnt vmcnt(3)
	v_pk_mul_f32 v[66:67], v[52:53], v[52:53]
	v_pk_mul_f32 v[68:69], v[50:51], v[50:51]
	s_waitcnt vmcnt(2)
	v_pk_mul_f32 v[70:71], v[56:57], v[56:57]
	v_pk_mul_f32 v[72:73], v[54:55], v[54:55]
	v_pk_mov_b32 v[78:79], v[68:69], v[66:67] op_sel:[1,0]
	v_mov_b32_e32 v69, v67
	v_pk_mov_b32 v[66:67], v[72:73], v[70:71] op_sel:[1,0]
	v_mov_b32_e32 v73, v71
	s_waitcnt vmcnt(1)
	v_mul_f32_e32 v77, v60, v60
	s_waitcnt vmcnt(0)
	v_mul_f32_e32 v74, v63, v63
	v_mul_f32_e32 v76, v65, v65
	v_pk_add_f32 v[68:69], v[78:79], v[68:69]
	v_pk_add_f32 v[66:67], v[66:67], v[72:73]
	v_mul_f32_e32 v49, v58, v58
	v_mul_f32_e32 v80, v61, v61
	v_mul_f32_e32 v81, v59, v59
	v_pk_fma_f32 v[70:71], v[62:63], v[62:63], v[74:75] op_sel_hi:[1,1,0]
	v_pk_fma_f32 v[74:75], v[64:65], v[64:65], v[76:77] op_sel_hi:[1,1,0]
	v_pk_add_f32 v[68:69], v[68:69], v[68:69] op_sel:[0,1] op_sel_hi:[1,0]
	v_pk_add_f32 v[66:67], v[66:67], v[66:67] op_sel:[0,1] op_sel_hi:[1,0]
	v_mov_b32_e32 v71, v77
	v_mov_b32_e32 v75, v80
	v_mov_b32_e32 v69, v49
	v_mov_b32_e32 v67, v81
	v_pk_add_f32 v[70:71], v[70:71], v[74:75]
	v_pk_add_f32 v[66:67], v[68:69], v[66:67]
	s_nop 0
	v_pk_add_f32 v[66:67], v[66:67], v[70:71]
	s_nop 0
	v_add_f32_e32 v49, v66, v67
	ds_bpermute_b32 v66, v1, v49
	s_waitcnt lgkmcnt(0)
	v_add_f32_e32 v49, v49, v66
	ds_bpermute_b32 v66, v35, v49
	s_waitcnt lgkmcnt(0)
	v_add_f32_e32 v49, v49, v66
	ds_bpermute_b32 v66, v40, v49
	s_waitcnt lgkmcnt(0)
	v_add_f32_e32 v49, v49, v66
	ds_bpermute_b32 v66, v41, v49
	s_waitcnt lgkmcnt(0)
	v_add_f32_e32 v49, v49, v66
	ds_bpermute_b32 v66, v42, v49
	s_waitcnt lgkmcnt(0)
	v_add_f32_e32 v49, v49, v66
	ds_bpermute_b32 v66, v43, v49
	s_waitcnt lgkmcnt(0)
	v_add_f32_e32 v49, v49, v66
	v_fmamk_f32 v49, v49, 0x3a800000, v47
	v_mul_f32_e32 v66, 0x4f800000, v49
	v_cmp_gt_f32_e32 vcc, s18, v49
	s_nop 1
	v_cndmask_b32_e32 v49, v49, v66, vcc
	v_sqrt_f32_e32 v66, v49
	s_nop 0
	v_add_u32_e32 v67, -1, v66
	v_add_u32_e32 v68, 1, v66
	v_fma_f32 v69, -v67, v66, v49
	v_fma_f32 v70, -v68, v66, v49
	v_cmp_ge_f32_e64 s[0:1], 0, v69
	s_nop 1
	v_cndmask_b32_e64 v66, v66, v67, s[0:1]
	v_cmp_lt_f32_e64 s[0:1], 0, v70
	s_nop 1
	v_cndmask_b32_e64 v66, v66, v68, s[0:1]
	v_mul_f32_e32 v67, 0x37800000, v66
	v_cndmask_b32_e32 v66, v66, v67, vcc
	v_cmp_class_f32_e32 vcc, v49, v48
	s_nop 1
	v_cndmask_b32_e32 v49, v66, v49, vcc
	v_div_scale_f32 v66, s[0:1], v49, v49, 1.0
	v_rcp_f32_e32 v67, v66
	v_div_scale_f32 v68, vcc, 1.0, v49, 1.0
	v_fma_f32 v69, -v66, v67, 1.0
	v_fmac_f32_e32 v67, v69, v67
	v_mul_f32_e32 v69, v68, v67
	v_fma_f32 v70, -v66, v69, v68
	v_fmac_f32_e32 v69, v70, v67
	v_fma_f32 v66, -v66, v69, v68
	v_div_fmas_f32 v66, v66, v67, v69
	v_div_fixup_f32 v66, v66, v49, 1.0
	v_pk_mul_f32 v[50:51], v[50:51], v[66:67] op_sel_hi:[1,0]
	v_pk_mul_f32 v[52:53], v[52:53], v[66:67] op_sel_hi:[1,0]
	v_pk_mul_f32 v[54:55], v[54:55], v[66:67] op_sel_hi:[1,0]
	v_pk_mul_f32 v[56:57], v[56:57], v[66:67] op_sel_hi:[1,0]
	v_pk_mul_f32 v[62:63], v[62:63], v[66:67] op_sel_hi:[1,0]
	v_pk_mul_f32 v[64:65], v[64:65], v[66:67] op_sel_hi:[1,0]
	v_pk_mul_f32 v[58:59], v[58:59], v[66:67] op_sel_hi:[1,0]
	v_pk_mul_f32 v[60:61], v[60:61], v[66:67] op_sel_hi:[1,0]
	v_pk_fma_f32 v[52:53], v[20:21], v[52:53], v[4:5]
	v_pk_fma_f32 v[50:51], v[18:19], v[50:51], v[2:3]
	v_pk_fma_f32 v[56:57], v[24:25], v[56:57], v[12:13]
	v_pk_fma_f32 v[54:55], v[22:23], v[54:55], v[10:11]
	v_pk_fma_f32 v[64:65], v[28:29], v[64:65], v[8:9]
	v_pk_fma_f32 v[62:63], v[26:27], v[62:63], v[6:7]
	v_pk_fma_f32 v[60:61], v[32:33], v[60:61], v[16:17]
	v_pk_fma_f32 v[58:59], v[30:31], v[58:59], v[14:15]
	v_cvt_pk_bf16_f32 v50, v50, v51
	v_cvt_pk_bf16_f32 v51, v52, v53
	v_cvt_pk_bf16_f32 v52, v54, v55
	v_cvt_pk_bf16_f32 v53, v56, v57
	v_cvt_pk_bf16_f32 v54, v62, v63
	v_cvt_pk_bf16_f32 v55, v64, v65
	v_cvt_pk_bf16_f32 v56, v58, v59
	v_cvt_pk_bf16_f32 v57, v60, v61
	global_store_dwordx2 v[38:39], v[50:51], off sc1
	global_store_dwordx2 v[38:39], v[52:53], off offset:512 sc1
	global_store_dwordx2 v[38:39], v[54:55], off offset:1024 sc1
	global_store_dwordx2 v[38:39], v[56:57], off offset:1536 sc1
	v_lshl_add_u64 v[38:39], v[38:39], 0, s[12:13]
	s_cbranch_scc0 .LBB0_100

.LBB0_385:
	v_add_co_u32_e32 v74, vcc, s20, v62
	s_and_b64 s[0:1], s[0:1], exec
	s_nop 0
	v_addc_co_u32_e32 v75, vcc, -1, v63, vcc
	global_load_dwordx2 v[78:79], v[74:75], off offset:-1536 nt
	global_load_dwordx2 v[80:81], v[74:75], off offset:-1024 nt
	global_load_dwordx2 v[82:83], v[74:75], off offset:-512 nt
	global_load_dwordx2 v[84:85], v[74:75], off nt
	s_cselect_b32 s1, s7, 0
	s_cselect_b32 s0, s6, s23
	s_cselect_b32 s14, s53, s55
	s_cselect_b32 s15, s52, s54
	s_lshl_b64 s[0:1], s[0:1], 12
	s_add_u32 s0, s15, s0
	s_addc_u32 s1, s14, s1
	global_load_dwordx4 v[74:77], v73, s[0:1]
	s_add_u32 s6, s6, s8
	s_addc_u32 s7, s7, s9
	s_cmp_lt_i32 s6, s98
	s_waitcnt vmcnt(0)
	v_and_b32_e32 v91, 0xffff0000, v78
	v_and_b32_e32 v93, 0xffff0000, v79
	v_lshlrev_b32_e32 v90, 16, v78
	v_lshlrev_b32_e32 v103, 16, v84
	v_lshlrev_b32_e32 v92, 16, v79
	v_and_b32_e32 v97, 0xffff0000, v81
	v_and_b32_e32 v96, 0xffff0000, v80
	v_lshlrev_b32_e32 v98, 16, v82
	v_and_b32_e32 v99, 0xffff0000, v82
	v_mul_f32_e32 v78, v93, v93
	v_mul_f32_e32 v82, v91, v91
	v_mov_b32_e32 v79, v103
	v_lshlrev_b32_e32 v95, 16, v81
	v_lshlrev_b32_e32 v94, 16, v80
	v_lshlrev_b32_e32 v100, 16, v83
	v_and_b32_e32 v101, 0xffff0000, v83
	v_pk_mul_f32 v[80:81], v[96:97], v[96:97]
	v_pk_fma_f32 v[88:89], v[92:93], v[92:93], v[78:79] op_sel_hi:[1,1,0]
	v_pk_fma_f32 v[82:83], v[90:91], v[90:91], v[82:83] op_sel_hi:[1,1,0]
	v_and_b32_e32 v105, 0xffff0000, v84
	v_lshlrev_b32_e32 v106, 16, v85
	v_and_b32_e32 v107, 0xffff0000, v85
	v_mul_f32_e32 v84, v99, v99
	v_mul_f32_e32 v86, v101, v101
	v_pk_fma_f32 v[80:81], v[94:95], v[94:95], v[80:81]
	v_mov_b32_e32 v102, v82
	v_mov_b32_e32 v78, v88
	v_mul_f32_e32 v104, v105, v105
	v_mul_f32_e32 v108, v106, v106
	v_mul_f32_e32 v109, v107, v107
	v_pk_fma_f32 v[84:85], v[98:99], v[98:99], v[84:85] op_sel_hi:[1,1,0]
	v_pk_fma_f32 v[86:87], v[100:101], v[100:101], v[86:87] op_sel_hi:[1,1,0]
	v_pk_add_f32 v[82:83], v[82:83], v[88:89]
	v_pk_add_f32 v[80:81], v[80:81], v[80:81] op_sel:[0,1] op_sel_hi:[1,0]
	v_pk_mul_f32 v[78:79], v[102:103], v[78:79]
	v_mov_b32_e32 v85, v108
	v_mov_b32_e32 v87, v109
	v_mov_b32_e32 v81, v104
	v_mov_b32_e32 v83, v79
	v_pk_add_f32 v[84:85], v[84:85], v[86:87]
	v_pk_add_f32 v[78:79], v[82:83], v[80:81]
	v_mov_b32_e32 v108, v94
	v_pk_add_f32 v[78:79], v[78:79], v[84:85]
	v_mov_b32_e32 v109, v96
	v_add_f32_e32 v102, v78, v79
	global_load_dwordx4 v[78:81], v73, s[0:1] offset:1024
	global_load_dwordx4 v[82:85], v73, s[0:1] offset:2048
	global_load_dwordx4 v[86:89], v73, s[0:1] offset:3072
	ds_bpermute_b32 v104, v1, v102
	v_mov_b32_e32 v96, v95
	s_waitcnt lgkmcnt(0)
	v_add_f32_e32 v73, v102, v104
	ds_bpermute_b32 v102, v51, v73
	s_waitcnt lgkmcnt(0)
	v_add_f32_e32 v73, v73, v102
	ds_bpermute_b32 v102, v64, v73
	s_waitcnt lgkmcnt(0)
	v_add_f32_e32 v73, v73, v102
	ds_bpermute_b32 v102, v65, v73
	s_waitcnt lgkmcnt(0)
	v_add_f32_e32 v73, v73, v102
	ds_bpermute_b32 v102, v66, v73
	s_waitcnt lgkmcnt(0)
	v_add_f32_e32 v73, v73, v102
	ds_bpermute_b32 v102, v67, v73
	s_waitcnt lgkmcnt(0)
	v_add_f32_e32 v73, v73, v102
	v_fmamk_f32 v73, v73, 0x3a800000, v71
	v_mul_f32_e32 v102, 0x4f800000, v73
	v_cmp_gt_f32_e32 vcc, s21, v73
	s_nop 1
	v_cndmask_b32_e32 v73, v73, v102, vcc
	v_sqrt_f32_e32 v102, v73
	s_nop 0
	v_add_u32_e32 v94, -1, v102
	v_add_u32_e32 v95, 1, v102
	v_fma_f32 v104, -v94, v102, v73
	v_fma_f32 v110, -v95, v102, v73
	v_cmp_ge_f32_e64 s[0:1], 0, v104
	v_mov_b32_e32 v104, v103
	s_nop 0
	v_cndmask_b32_e64 v94, v102, v94, s[0:1]
	v_cmp_lt_f32_e64 s[0:1], 0, v110
	s_nop 1
	v_cndmask_b32_e64 v94, v94, v95, s[0:1]
	v_mul_f32_e32 v95, 0x37800000, v94
	v_cndmask_b32_e32 v94, v94, v95, vcc
	v_cmp_class_f32_e32 vcc, v73, v72
	s_nop 1
	v_cndmask_b32_e32 v73, v94, v73, vcc
	v_div_scale_f32 v94, s[0:1], v73, v73, 1.0
	v_rcp_f32_e32 v95, v94
	v_div_scale_f32 v102, vcc, 1.0, v73, 1.0
	v_fma_f32 v103, -v94, v95, 1.0
	v_fmac_f32_e32 v95, v103, v95
	v_mul_f32_e32 v103, v102, v95
	v_fma_f32 v110, -v94, v103, v102
	v_fmac_f32_e32 v103, v110, v95
	v_fma_f32 v94, -v94, v103, v102
	v_div_fmas_f32 v94, v94, v95, v103
	v_div_fixup_f32 v94, v94, v73, 1.0
	v_pk_mul_f32 v[90:91], v[94:95], v[90:91] op_sel_hi:[0,1]
	v_pk_mul_f32 v[92:93], v[94:95], v[92:93] op_sel_hi:[0,1]
	v_pk_mul_f32 v[102:103], v[94:95], v[108:109] op_sel_hi:[0,1]
	v_pk_mul_f32 v[96:97], v[94:95], v[96:97] op_sel_hi:[0,1]
	v_pk_mul_f32 v[98:99], v[94:95], v[98:99] op_sel_hi:[0,1]
	v_pk_mul_f32 v[100:101], v[94:95], v[100:101] op_sel_hi:[0,1]
	v_pk_mul_f32 v[104:105], v[104:105], v[94:95] op_sel_hi:[1,0]
	v_pk_mul_f32 v[94:95], v[106:107], v[94:95] op_sel_hi:[1,0]
	v_pk_fma_f32 v[76:77], v[16:17], v[92:93], v[76:77]
	v_pk_fma_f32 v[74:75], v[14:15], v[90:91], v[74:75]
	s_waitcnt vmcnt(2)
	v_pk_fma_f32 v[80:81], v[28:29], v[96:97], v[80:81]
	v_pk_fma_f32 v[78:79], v[26:27], v[102:103], v[78:79]
	s_waitcnt vmcnt(0)
	v_pk_fma_f32 v[88:89], v[24:25], v[94:95], v[88:89]
	v_pk_mul_f32 v[90:91], v[76:77], v[76:77]
	v_pk_mul_f32 v[92:93], v[74:75], v[74:75]
	v_pk_mul_f32 v[94:95], v[80:81], v[80:81]
	v_pk_mul_f32 v[96:97], v[78:79], v[78:79]
	v_pk_fma_f32 v[84:85], v[32:33], v[100:101], v[84:85]
	v_pk_fma_f32 v[82:83], v[30:31], v[98:99], v[82:83]
	v_pk_mov_b32 v[102:103], v[92:93], v[90:91] op_sel:[1,0]
	v_mov_b32_e32 v93, v91
	v_pk_mov_b32 v[90:91], v[96:97], v[94:95] op_sel:[1,0]
	v_mov_b32_e32 v97, v95
	v_mul_f32_e32 v98, v82, v82
	v_mul_f32_e32 v100, v84, v84
	v_pk_add_f32 v[92:93], v[102:103], v[92:93]
	v_pk_add_f32 v[90:91], v[90:91], v[96:97]
	v_pk_fma_f32 v[86:87], v[22:23], v[104:105], v[86:87]
	v_pk_fma_f32 v[94:95], v[82:83], v[82:83], v[98:99] op_sel_hi:[1,1,0]
	v_pk_fma_f32 v[98:99], v[84:85], v[84:85], v[100:101] op_sel_hi:[1,1,0]
	v_pk_add_f32 v[92:93], v[92:93], v[92:93] op_sel_hi:[0,1]
	v_pk_add_f32 v[90:91], v[90:91], v[90:91] op_sel_hi:[0,1]
	v_mul_f32_e32 v94, v86, v86
	v_mul_f32_e32 v98, v87, v87
	v_mul_f32_e32 v92, v88, v88
	v_mul_f32_e32 v90, v89, v89
	v_pk_add_f32 v[94:95], v[94:95], v[98:99]
	v_pk_add_f32 v[90:91], v[92:93], v[90:91]
	v_cvt_pk_bf16_f32 v93, v76, v77
	v_pk_add_f32 v[90:91], v[94:95], v[90:91]
	v_cvt_pk_bf16_f32 v94, v78, v79
	v_add_f32_e32 v73, v90, v91
	ds_bpermute_b32 v90, v1, v73
	v_cvt_pk_bf16_f32 v95, v80, v81
	v_cvt_pk_bf16_f32 v97, v84, v85
	v_cvt_pk_bf16_f32 v98, v86, v87
	v_cvt_pk_bf16_f32 v99, v88, v89
	s_waitcnt lgkmcnt(0)
	v_add_f32_e32 v73, v73, v90
	ds_bpermute_b32 v90, v51, v73
	s_waitcnt lgkmcnt(0)
	v_add_f32_e32 v73, v73, v90
	ds_bpermute_b32 v90, v64, v73
	s_waitcnt lgkmcnt(0)
	v_add_f32_e32 v73, v73, v90
	ds_bpermute_b32 v92, v65, v73
	v_add_co_u32_e32 v90, vcc, s22, v62
	s_waitcnt lgkmcnt(0)
	v_add_f32_e32 v73, v73, v92
	ds_bpermute_b32 v96, v66, v73
	v_addc_co_u32_e32 v91, vcc, -1, v63, vcc
	v_cvt_pk_bf16_f32 v92, v74, v75
	s_waitcnt lgkmcnt(0)
	v_add_f32_e32 v73, v73, v96
	ds_bpermute_b32 v100, v67, v73
	v_cvt_pk_bf16_f32 v96, v82, v83
	global_store_dwordx2 v[62:63], v[92:93], off offset:-1536 sc1
	global_store_dwordx2 v[62:63], v[94:95], off offset:-1024 sc1
	global_store_dwordx2 v[62:63], v[96:97], off offset:-512 sc1
	global_store_dwordx2 v[62:63], v[98:99], off sc1
	v_lshl_add_u64 v[62:63], v[62:63], 0, s[12:13]
	s_waitcnt lgkmcnt(0)
	v_add_f32_e32 v73, v73, v100
	v_fmamk_f32 v73, v73, 0x3a800000, v71
	v_mul_f32_e32 v100, 0x4f800000, v73
	v_cmp_gt_f32_e32 vcc, s21, v73
	s_nop 1
	v_cndmask_b32_e32 v73, v73, v100, vcc
	v_sqrt_f32_e32 v100, v73
	s_nop 0
	v_add_u32_e32 v92, -1, v100
	v_add_u32_e32 v93, 1, v100
	v_fma_f32 v94, -v92, v100, v73
	v_fma_f32 v95, -v93, v100, v73
	v_cmp_ge_f32_e64 s[0:1], 0, v94
	s_nop 1
	v_cndmask_b32_e64 v92, v100, v92, s[0:1]
	v_cmp_lt_f32_e64 s[0:1], 0, v95
	s_nop 1
	v_cndmask_b32_e64 v92, v92, v93, s[0:1]
	v_mul_f32_e32 v93, 0x37800000, v92
	v_cndmask_b32_e32 v92, v92, v93, vcc
	v_cmp_class_f32_e32 vcc, v73, v72
	s_nop 1
	v_cndmask_b32_e32 v73, v92, v73, vcc
	v_div_scale_f32 v92, s[0:1], v73, v73, 1.0
	v_rcp_f32_e32 v93, v92
	v_div_scale_f32 v94, vcc, 1.0, v73, 1.0
	v_fma_f32 v95, -v92, v93, 1.0
	v_fmac_f32_e32 v93, v95, v93
	v_mul_f32_e32 v95, v94, v93
	v_fma_f32 v96, -v92, v95, v94
	v_fmac_f32_e32 v95, v96, v93
	v_fma_f32 v92, -v92, v95, v94
	v_div_fmas_f32 v92, v92, v93, v95
	v_div_fixup_f32 v92, v92, v73, 1.0
	v_pk_mul_f32 v[74:75], v[74:75], v[92:93] op_sel_hi:[1,0]
	v_pk_mul_f32 v[76:77], v[76:77], v[92:93] op_sel_hi:[1,0]
	v_pk_mul_f32 v[78:79], v[78:79], v[92:93] op_sel_hi:[1,0]
	v_pk_mul_f32 v[80:81], v[80:81], v[92:93] op_sel_hi:[1,0]
	v_pk_mul_f32 v[82:83], v[82:83], v[92:93] op_sel_hi:[1,0]
	v_pk_mul_f32 v[84:85], v[84:85], v[92:93] op_sel_hi:[1,0]
	v_pk_fma_f32 v[76:77], v[36:37], v[76:77], v[20:21]
	v_pk_fma_f32 v[74:75], v[34:35], v[74:75], v[18:19]
	v_pk_fma_f32 v[80:81], v[40:41], v[80:81], v[4:5]
	v_pk_fma_f32 v[78:79], v[38:39], v[78:79], v[2:3]
	v_pk_fma_f32 v[84:85], v[44:45], v[84:85], v[12:13]
	v_pk_fma_f32 v[82:83], v[42:43], v[82:83], v[10:11]
	v_cvt_pk_bf16_f32 v74, v74, v75
	v_cvt_pk_bf16_f32 v75, v76, v77
	v_cvt_pk_bf16_f32 v76, v78, v79
	v_cvt_pk_bf16_f32 v77, v80, v81
	v_cvt_pk_bf16_f32 v78, v82, v83
	v_cvt_pk_bf16_f32 v79, v84, v85
	global_store_dwordx2 v[90:91], v[74:75], off offset:-1536 sc1
	global_store_dwordx2 v[90:91], v[76:77], off offset:-1024 sc1
	global_store_dwordx2 v[90:91], v[78:79], off offset:-512 sc1
	v_pk_mul_f32 v[74:75], v[86:87], v[92:93] op_sel_hi:[1,0]
	v_pk_mul_f32 v[76:77], v[88:89], v[92:93] op_sel_hi:[1,0]
	v_pk_fma_f32 v[74:75], v[46:47], v[74:75], v[6:7]
	v_pk_fma_f32 v[76:77], v[48:49], v[76:77], v[8:9]
	v_cvt_pk_bf16_f32 v74, v74, v75
	v_cvt_pk_bf16_f32 v75, v76, v77
	global_store_dwordx2 v[90:91], v[74:75], off sc1
	s_cbranch_scc0 .LBB0_388

.LBB0_904:
	global_load_dwordx2 v[82:83], v[66:67], off nt
	global_load_dwordx2 v[84:85], v[66:67], off offset:512 nt
	global_load_dwordx2 v[86:87], v[66:67], off offset:1024 nt
	global_load_dwordx2 v[88:89], v[66:67], off offset:1536 nt
	v_add_co_u32_e32 v68, vcc, 0x2800000, v66
	s_add_i32 s6, s6, s8
	s_nop 0
	v_addc_co_u32_e32 v69, vcc, 0, v67, vcc
	global_load_dwordx2 v[90:91], v[68:69], off nt
	global_load_dwordx2 v[92:93], v[68:69], off offset:512 nt
	global_load_dwordx2 v[94:95], v[68:69], off offset:1024 nt
	global_load_dwordx2 v[96:97], v[68:69], off offset:1536 nt
	s_cmp_lt_i32 s6, s98
	s_waitcnt vmcnt(0)
	v_lshlrev_b32_e32 v98, 16, v82
	v_and_b32_e32 v99, 0xffff0000, v82
	v_lshlrev_b32_e32 v82, 16, v83
	v_and_b32_e32 v83, 0xffff0000, v83
	v_lshlrev_b32_e32 v101, 16, v85
	v_lshlrev_b32_e32 v100, 16, v84
	v_and_b32_e32 v85, 0xffff0000, v85
	v_and_b32_e32 v84, 0xffff0000, v84
	v_and_b32_e32 v103, 0xffff0000, v86
	v_lshlrev_b32_e32 v105, 16, v88
	v_and_b32_e32 v107, 0xffff0000, v88
	v_mul_f32_e32 v104, v83, v83
	v_mul_f32_e32 v106, v99, v99
	v_lshlrev_b32_e32 v102, 16, v86
	v_lshlrev_b32_e32 v86, 16, v87
	v_and_b32_e32 v87, 0xffff0000, v87
	v_pk_mul_f32 v[108:109], v[84:85], v[84:85]
	v_mov_b32_e32 v111, v105
	v_mul_f32_e32 v110, v103, v103
	v_pk_fma_f32 v[114:115], v[82:83], v[82:83], v[104:105] op_sel_hi:[1,1,0]
	v_pk_fma_f32 v[116:117], v[98:99], v[98:99], v[106:107] op_sel_hi:[1,1,0]
	v_lshlrev_b32_e32 v88, 16, v89
	v_and_b32_e32 v89, 0xffff0000, v89
	v_mul_f32_e32 v112, v87, v87
	v_pk_fma_f32 v[108:109], v[100:101], v[100:101], v[108:109]
	v_pk_fma_f32 v[118:119], v[102:103], v[102:103], v[110:111] op_sel_hi:[1,1,0]
	v_mov_b32_e32 v104, v116
	v_mov_b32_e32 v110, v114
	v_mul_f32_e32 v81, v107, v107
	v_mul_f32_e32 v120, v88, v88
	v_mul_f32_e32 v121, v89, v89
	v_pk_fma_f32 v[112:113], v[86:87], v[86:87], v[112:113] op_sel_hi:[1,1,0]
	v_pk_add_f32 v[114:115], v[116:117], v[114:115]
	v_pk_add_f32 v[108:109], v[108:109], v[108:109] op_sel:[0,1] op_sel_hi:[1,0]
	v_pk_mul_f32 v[110:111], v[104:105], v[110:111]
	v_mov_b32_e32 v119, v120
	v_mov_b32_e32 v113, v121
	v_mov_b32_e32 v109, v81
	v_mov_b32_e32 v115, v111
	v_pk_add_f32 v[112:113], v[118:119], v[112:113]
	v_pk_add_f32 v[108:109], v[114:115], v[108:109]
	v_mov_b32_e32 v106, v105
	v_pk_add_f32 v[108:109], v[108:109], v[112:113]
	v_and_b32_e32 v105, 0xffff0000, v92
	v_add_f32_e32 v81, v108, v109
	ds_bpermute_b32 v104, v1, v81
	v_mov_b32_e32 v108, v100
	v_mov_b32_e32 v109, v84
	v_mov_b32_e32 v84, v101
	v_lshlrev_b32_e32 v100, 16, v90
	s_waitcnt lgkmcnt(0)
	v_add_f32_e32 v81, v81, v104
	ds_bpermute_b32 v104, v70, v81
	v_and_b32_e32 v101, 0xffff0000, v90
	v_lshlrev_b32_e32 v90, 16, v91
	v_and_b32_e32 v91, 0xffff0000, v91
	v_and_b32_e32 v111, 0xffff0000, v94
	s_waitcnt lgkmcnt(0)
	v_add_f32_e32 v81, v81, v104
	ds_bpermute_b32 v104, v71, v81
	v_and_b32_e32 v113, 0xffff0000, v96
	s_waitcnt lgkmcnt(0)
	v_add_f32_e32 v81, v81, v104
	ds_bpermute_b32 v104, v72, v81
	s_waitcnt lgkmcnt(0)
	v_add_f32_e32 v81, v81, v104
	ds_bpermute_b32 v110, v73, v81
	v_lshlrev_b32_e32 v104, 16, v92
	v_lshlrev_b32_e32 v92, 16, v93
	v_and_b32_e32 v93, 0xffff0000, v93
	s_waitcnt lgkmcnt(0)
	v_add_f32_e32 v81, v81, v110
	ds_bpermute_b32 v112, v74, v81
	v_lshlrev_b32_e32 v110, 16, v94
	v_lshlrev_b32_e32 v94, 16, v95
	v_and_b32_e32 v95, 0xffff0000, v95
	s_waitcnt lgkmcnt(0)
	v_add_f32_e32 v81, v81, v112
	v_fmamk_f32 v81, v81, 0x3a800000, v79
	v_mul_f32_e32 v112, 0x4f800000, v81
	v_cmp_gt_f32_e32 vcc, s7, v81
	s_nop 1
	v_cndmask_b32_e32 v81, v81, v112, vcc
	v_sqrt_f32_e32 v114, v81
	v_lshlrev_b32_e32 v112, 16, v96
	v_lshlrev_b32_e32 v96, 16, v97
	v_and_b32_e32 v97, 0xffff0000, v97
	v_add_u32_e32 v115, -1, v114
	v_add_u32_e32 v116, 1, v114
	v_fma_f32 v117, -v115, v114, v81
	v_fma_f32 v118, -v116, v114, v81
	v_cmp_ge_f32_e64 s[0:1], 0, v117
	s_nop 1
	v_cndmask_b32_e64 v114, v114, v115, s[0:1]
	v_cmp_lt_f32_e64 s[0:1], 0, v118
	s_nop 1
	v_cndmask_b32_e64 v114, v114, v116, s[0:1]
	v_mul_f32_e32 v115, 0x37800000, v114
	v_cndmask_b32_e32 v114, v114, v115, vcc
	v_cmp_class_f32_e32 vcc, v81, v80
	s_nop 1
	v_cndmask_b32_e32 v81, v114, v81, vcc
	v_div_scale_f32 v114, s[0:1], v81, v81, 1.0
	v_rcp_f32_e32 v115, v114
	v_div_scale_f32 v116, vcc, 1.0, v81, 1.0
	v_fma_f32 v117, -v114, v115, 1.0
	v_fmac_f32_e32 v115, v117, v115
	v_mul_f32_e32 v117, v116, v115
	v_fma_f32 v118, -v114, v117, v116
	v_fmac_f32_e32 v117, v118, v115
	v_fma_f32 v114, -v114, v117, v116
	v_div_fmas_f32 v114, v114, v115, v117
	v_div_fixup_f32 v114, v114, v81, 1.0
	v_pk_mul_f32 v[98:99], v[114:115], v[98:99] op_sel_hi:[0,1]
	v_pk_mul_f32 v[82:83], v[114:115], v[82:83] op_sel_hi:[0,1]
	v_pk_mul_f32 v[108:109], v[114:115], v[108:109] op_sel_hi:[0,1]
	v_pk_mul_f32 v[84:85], v[114:115], v[84:85] op_sel_hi:[0,1]
	v_pk_mul_f32 v[102:103], v[114:115], v[102:103] op_sel_hi:[0,1]
	v_pk_mul_f32 v[86:87], v[114:115], v[86:87] op_sel_hi:[0,1]
	v_pk_fma_f32 v[82:83], v[20:21], v[82:83], v[90:91]
	v_pk_fma_f32 v[90:91], v[18:19], v[98:99], v[100:101]
	v_pk_fma_f32 v[84:85], v[28:29], v[84:85], v[92:93]
	v_pk_fma_f32 v[92:93], v[26:27], v[108:109], v[104:105]
	v_pk_fma_f32 v[86:87], v[16:17], v[86:87], v[94:95]
	v_pk_fma_f32 v[94:95], v[14:15], v[102:103], v[110:111]
	v_pk_mul_f32 v[98:99], v[82:83], v[82:83]
	v_pk_mul_f32 v[100:101], v[90:91], v[90:91]
	v_pk_mul_f32 v[102:103], v[84:85], v[84:85]
	v_pk_mul_f32 v[104:105], v[92:93], v[92:93]
	v_pk_mul_f32 v[106:107], v[106:107], v[114:115] op_sel_hi:[1,0]
	v_pk_mul_f32 v[88:89], v[88:89], v[114:115] op_sel_hi:[1,0]
	v_pk_mov_b32 v[110:111], v[100:101], v[98:99] op_sel:[1,0]
	v_mov_b32_e32 v101, v99
	v_pk_mov_b32 v[98:99], v[104:105], v[102:103] op_sel:[1,0]
	v_mov_b32_e32 v105, v103
	v_pk_fma_f32 v[88:89], v[32:33], v[88:89], v[96:97]
	v_pk_fma_f32 v[96:97], v[30:31], v[106:107], v[112:113]
	v_mul_f32_e32 v106, v94, v94
	v_mul_f32_e32 v108, v86, v86
	v_pk_add_f32 v[100:101], v[110:111], v[100:101]
	v_pk_add_f32 v[98:99], v[98:99], v[104:105]
	v_pk_fma_f32 v[102:103], v[94:95], v[94:95], v[106:107] op_sel_hi:[1,1,0]
	v_pk_fma_f32 v[106:107], v[86:87], v[86:87], v[108:109] op_sel_hi:[1,1,0]
	v_pk_add_f32 v[100:101], v[100:101], v[100:101] op_sel_hi:[0,1]
	v_pk_add_f32 v[98:99], v[98:99], v[98:99] op_sel_hi:[0,1]
	v_mul_f32_e32 v102, v96, v96
	v_mul_f32_e32 v106, v97, v97
	v_mul_f32_e32 v100, v88, v88
	v_mul_f32_e32 v98, v89, v89
	v_pk_add_f32 v[102:103], v[102:103], v[106:107]
	v_pk_add_f32 v[98:99], v[100:101], v[98:99]
	v_cvt_pk_bf16_f32 v101, v82, v83
	v_pk_add_f32 v[98:99], v[102:103], v[98:99]
	v_cvt_pk_bf16_f32 v102, v92, v93
	v_add_f32_e32 v81, v98, v99
	ds_bpermute_b32 v98, v1, v81
	v_cvt_pk_bf16_f32 v103, v84, v85
	v_cvt_pk_bf16_f32 v105, v86, v87
	v_cvt_pk_bf16_f32 v106, v96, v97
	v_cvt_pk_bf16_f32 v107, v88, v89
	s_waitcnt lgkmcnt(0)
	v_add_f32_e32 v81, v81, v98
	ds_bpermute_b32 v98, v70, v81
	s_waitcnt lgkmcnt(0)
	v_add_f32_e32 v81, v81, v98
	ds_bpermute_b32 v98, v71, v81
	s_waitcnt lgkmcnt(0)
	v_add_f32_e32 v81, v81, v98
	ds_bpermute_b32 v100, v72, v81
	v_add_co_u32_e32 v98, vcc, s9, v66
	s_waitcnt lgkmcnt(0)
	v_add_f32_e32 v81, v81, v100
	ds_bpermute_b32 v104, v73, v81
	v_addc_co_u32_e32 v99, vcc, -1, v67, vcc
	v_cvt_pk_bf16_f32 v100, v90, v91
	s_waitcnt lgkmcnt(0)
	v_add_f32_e32 v81, v81, v104
	ds_bpermute_b32 v108, v74, v81
	v_cvt_pk_bf16_f32 v104, v94, v95
	global_store_dwordx2 v[68:69], v[100:101], off sc1
	global_store_dwordx2 v[68:69], v[102:103], off offset:512 sc1
	global_store_dwordx2 v[68:69], v[104:105], off offset:1024 sc1
	global_store_dwordx2 v[68:69], v[106:107], off offset:1536 sc1
	s_waitcnt lgkmcnt(0)
	v_add_f32_e32 v81, v81, v108
	v_fmamk_f32 v81, v81, 0x3a800000, v79
	v_mul_f32_e32 v108, 0x4f800000, v81
	v_cmp_gt_f32_e32 vcc, s7, v81
	s_nop 1
	v_cndmask_b32_e32 v81, v81, v108, vcc
	v_sqrt_f32_e32 v108, v81
	s_nop 0
	v_add_u32_e32 v100, -1, v108
	v_add_u32_e32 v101, 1, v108
	v_fma_f32 v102, -v100, v108, v81
	v_fma_f32 v103, -v101, v108, v81
	v_cmp_ge_f32_e64 s[0:1], 0, v102
	s_nop 1
	v_cndmask_b32_e64 v100, v108, v100, s[0:1]
	v_cmp_lt_f32_e64 s[0:1], 0, v103
	s_nop 1
	v_cndmask_b32_e64 v100, v100, v101, s[0:1]
	v_mul_f32_e32 v101, 0x37800000, v100
	v_cndmask_b32_e32 v100, v100, v101, vcc
	v_cmp_class_f32_e32 vcc, v81, v80
	s_nop 1
	v_cndmask_b32_e32 v81, v100, v81, vcc
	v_div_scale_f32 v100, s[0:1], v81, v81, 1.0
	v_rcp_f32_e32 v101, v100
	v_div_scale_f32 v68, vcc, 1.0, v81, 1.0
	v_fma_f32 v69, -v100, v101, 1.0
	v_fmac_f32_e32 v101, v69, v101
	v_mul_f32_e32 v69, v68, v101
	v_fma_f32 v102, -v100, v69, v68
	v_fmac_f32_e32 v69, v102, v101
	v_fma_f32 v68, -v100, v69, v68
	v_div_fmas_f32 v68, v68, v101, v69
	v_div_fixup_f32 v68, v68, v81, 1.0
	v_pk_mul_f32 v[90:91], v[90:91], v[68:69] op_sel_hi:[1,0]
	v_pk_mul_f32 v[82:83], v[82:83], v[68:69] op_sel_hi:[1,0]
	v_pk_mul_f32 v[84:85], v[84:85], v[68:69] op_sel_hi:[1,0]
	v_pk_mul_f32 v[92:93], v[92:93], v[68:69] op_sel_hi:[1,0]
	v_pk_fma_f32 v[82:83], v[36:37], v[82:83], v[8:9]
	v_pk_fma_f32 v[90:91], v[34:35], v[90:91], v[6:7]
	v_pk_fma_f32 v[84:85], v[40:41], v[84:85], v[12:13]
	v_pk_fma_f32 v[92:93], v[38:39], v[92:93], v[10:11]
	v_cvt_pk_bf16_f32 v90, v90, v91
	v_cvt_pk_bf16_f32 v91, v82, v83
	v_cvt_pk_bf16_f32 v83, v84, v85
	v_add_co_u32_e32 v84, vcc, s22, v66
	v_cvt_pk_bf16_f32 v82, v92, v93
	s_nop 0
	v_addc_co_u32_e32 v85, vcc, -1, v67, vcc
	global_store_dwordx2 v[84:85], v[82:83], off offset:-3584 sc1
	v_pk_mul_f32 v[82:83], v[94:95], v[68:69] op_sel_hi:[1,0]
	v_pk_mul_f32 v[86:87], v[86:87], v[68:69] op_sel_hi:[1,0]
	v_pk_fma_f32 v[82:83], v[42:43], v[82:83], v[2:3]
	v_pk_fma_f32 v[86:87], v[44:45], v[86:87], v[4:5]
	v_cvt_pk_bf16_f32 v82, v82, v83
	v_cvt_pk_bf16_f32 v83, v86, v87
	global_store_dwordx2 v[84:85], v[82:83], off offset:-3072 sc1
	v_pk_mul_f32 v[82:83], v[96:97], v[68:69] op_sel_hi:[1,0]
	v_pk_mul_f32 v[68:69], v[88:89], v[68:69] op_sel_hi:[1,0]
	v_pk_fma_f32 v[82:83], v[46:47], v[82:83], v[22:23]
	v_pk_fma_f32 v[68:69], v[48:49], v[68:69], v[24:25]
	v_cvt_pk_bf16_f32 v82, v82, v83
	v_cvt_pk_bf16_f32 v83, v68, v69
	v_lshl_add_u64 v[66:67], v[66:67], 0, s[12:13]
	global_store_dwordx2 v[98:99], v[90:91], off sc1
	global_store_dwordx2 v[84:85], v[82:83], off offset:-2560 sc1
	s_cbranch_scc0 .LBB0_907
